# MLA loop: deferred row-sum adds moved under the top-of-tile K/Qb LDS read latency
# speedup vs baseline: 1.0045x; 1.0015x over previous
; #define ALAS __attribute__((address_space(3)))
; #define AMFMA(a, b, c) __builtin_amdgcn_mfma_f32_32x32x16_bf16((a), (b), (c), 0, 0, 0)
; template <bool SUB> __device__ __forceinline__ void attn_unit_r2b(const AU& u, ALAS unsigned char* lds, float mb2) {
;     ...
;         if (t + 1 < NT) { const size_t ro = (size_t)(t + 1) * 64; rk0 = *(const u32x4*)(kg0 + ro * u.krs); if (k2) rk1 = *(const u32x4*)(kg1 + ro * u.krs); rv = *(const u32x4*)(vg + ro * u.vrs); }
;         {
;             const ALAS unsigned char* kb = lds + cur * KBUF + r * KP + h * 16;
;             const ALAS unsigned char* vb = lds + V_OFF + cur * VBUF + (4 * h + ((lane & 15) >> 2)) * VP + ((lane >> 4) & 1) * 32 + (lane & 3) * 8;
;             bf16x8 paa[4], pab[4];
;             f32x16 Sa0, Sa1, Sb0, Sb1;
; #pragma unroll
;             for (int i = 0; i < 16; ++i) { Sa0[i] = 0.f; Sa1[i] = 0.f; Sb0[i] = 0.f; Sb1[i] = 0.f; }
; #pragma unroll
;             for (int d0 = 0; d0 < 6; ++d0) {
;                 const bf16x8 k0 = *(const ALAS bf16x8*)(kb + d0 * 32), k1 = *(const ALAS bf16x8*)(kb + 32 * KP + d0 * 32); const bf16x8 qbv = *(const ALAS bf16x8*)(qbl + d0 * 1024);
;                 Sa0 = AMFMA(k0, qa[d0], Sa0); Sa1 = AMFMA(k1, qa[d0], Sa1); Sb0 = AMFMA(k0, qbv, Sb0); Sb1 = AMFMA(k1, qbv, Sb1);
;                 if (d0 & 1) __builtin_amdgcn_sched_barrier(0);
;             }
.Lr2b_nok2A:
	s_or_b64 exec, exec, s[58:59]
	global_load_dwordx4 v[160:163], v[166:167], off
	ds_read_b128 v[218:221], v168 offset:0
	ds_read_b128 v[222:225], v168 offset:32
	ds_read_b128 v[226:229], v168 offset:64
	ds_read_b128 v[230:233], v168 offset:96
	ds_read_b128 v[234:237], v168 offset:128
	ds_read_b128 v[238:241], v168 offset:160
	ds_read_b128 v[176:179], v193 offset:45056
	ds_read_b128 v[180:183], v193 offset:46080
	ds_read_b128 v[184:187], v193 offset:47104
	ds_read_b128 v[248:251], v193 offset:48128
	ds_read_b128 v[244:247], v193 offset:49152
	v_add_f32_e32 v242, v112, v242
	v_add_f32_e32 v243, v80, v243
	v_add_f32_e32 v242, v113, v242
	v_add_f32_e32 v243, v81, v243
	v_add_f32_e32 v242, v114, v242
	v_add_f32_e32 v243, v82, v243
	v_add_f32_e32 v242, v115, v242
	v_add_f32_e32 v243, v83, v243
	v_add_f32_e32 v242, v116, v242
	v_add_f32_e32 v243, v84, v243
	v_add_f32_e32 v242, v117, v242
	v_add_f32_e32 v243, v85, v243
	v_add_f32_e32 v242, v118, v242
	v_add_f32_e32 v243, v86, v243
	v_add_f32_e32 v242, v119, v242
	v_add_f32_e32 v243, v87, v243
	v_add_f32_e32 v242, v120, v242
	v_add_f32_e32 v243, v88, v243
	v_add_f32_e32 v242, v121, v242
	v_add_f32_e32 v243, v89, v243
	s_waitcnt lgkmcnt(5)
	v_mfma_f32_32x32x16_bf16 v[96:111], v[218:221], v[128:131], 0
	v_lshl_add_u64 v[166:167], v[166:167], 0, s[8:9]
	v_mfma_f32_32x32x16_bf16 v[96:111], v[222:225], v[132:135], v[96:111]
	v_lshl_add_u64 v[172:173], v[172:173], 0, s[12:13]
	v_mfma_f32_32x32x16_bf16 v[96:111], v[226:229], v[136:139], v[96:111]
	v_lshl_add_u64 v[174:175], v[174:175], 0, s[12:13]
	v_mfma_f32_32x32x16_bf16 v[96:111], v[230:233], v[140:143], v[96:111]
	v_mfma_f32_32x32x16_bf16 v[96:111], v[234:237], v[144:147], v[96:111]
	v_add_f32_e32 v242, v122, v242
	v_add_f32_e32 v243, v90, v243
	v_add_f32_e32 v242, v123, v242
	v_add_f32_e32 v243, v91, v243
	v_mfma_f32_32x32x16_bf16 v[96:111], v[238:241], v[148:151], v[96:111]
	v_add_f32_e32 v242, v124, v242
	v_add_f32_e32 v243, v92, v243
	v_add_f32_e32 v242, v125, v242
	v_add_f32_e32 v243, v93, v243
	s_waitcnt lgkmcnt(0)
	v_mfma_f32_32x32x16_bf16 v[64:79], v[218:221], v[176:179], 0
	ds_read_b128 v[176:179], v193 offset:50176
	ds_read_b128 v[218:221], v168 offset:6656
	v_add_f32_e32 v242, v126, v242
	v_add_f32_e32 v243, v94, v243
	v_add_f32_e32 v242, v127, v242
	v_add_f32_e32 v243, v95, v243
	v_mfma_f32_32x32x16_bf16 v[64:79], v[222:225], v[180:183], v[64:79]
	ds_read_b128 v[222:225], v168 offset:6688
	v_exp_f32_e32 v96, v96
	v_exp_f32_e32 v97, v97
	v_mfma_f32_32x32x16_bf16 v[64:79], v[226:229], v[184:187], v[64:79]
	ds_read_b128 v[226:229], v168 offset:6720
	v_exp_f32_e32 v98, v98
	v_exp_f32_e32 v99, v99
	v_mfma_f32_32x32x16_bf16 v[64:79], v[230:233], v[248:251], v[64:79]
	ds_read_b128 v[230:233], v168 offset:6752
	v_exp_f32_e32 v100, v100
	v_exp_f32_e32 v101, v101
	v_mfma_f32_32x32x16_bf16 v[64:79], v[234:237], v[244:247], v[64:79]
	ds_read_b128 v[234:237], v168 offset:6784
	v_exp_f32_e32 v102, v102
	v_exp_f32_e32 v103, v103
	s_waitcnt lgkmcnt(5)
	v_mfma_f32_32x32x16_bf16 v[64:79], v[238:241], v[176:179], v[64:79]
	ds_read_b128 v[238:241], v168 offset:6816
	ds_read_b128 v[176:179], v193 offset:45056
	v_exp_f32_e32 v104, v104
	v_exp_f32_e32 v105, v105
	v_exp_f32_e32 v106, v106
	v_exp_f32_e32 v107, v107
	s_waitcnt lgkmcnt(1)
	v_mfma_f32_32x32x16_bf16 v[112:127], v[218:221], v[128:131], 0
	v_exp_f32_e32 v108, v108
	v_exp_f32_e32 v109, v109
	v_exp_f32_e32 v110, v110
	v_exp_f32_e32 v111, v111
	v_mfma_f32_32x32x16_bf16 v[112:127], v[222:225], v[132:135], v[112:127]
	v_exp_f32_e32 v64, v64
	v_exp_f32_e32 v65, v65
	v_exp_f32_e32 v66, v66
	v_mfma_f32_32x32x16_bf16 v[112:127], v[226:229], v[136:139], v[112:127]
	v_exp_f32_e32 v67, v67
	v_exp_f32_e32 v68, v68
	v_exp_f32_e32 v69, v69
	v_mfma_f32_32x32x16_bf16 v[112:127], v[230:233], v[140:143], v[112:127]
	v_exp_f32_e32 v70, v70
	v_exp_f32_e32 v71, v71
	v_exp_f32_e32 v72, v72
	v_mfma_f32_32x32x16_bf16 v[112:127], v[234:237], v[144:147], v[112:127]
	v_exp_f32_e32 v73, v73
	v_exp_f32_e32 v74, v74
	v_exp_f32_e32 v75, v75
	v_mfma_f32_32x32x16_bf16 v[112:127], v[238:241], v[148:151], v[112:127]
	v_exp_f32_e32 v76, v76
	v_exp_f32_e32 v77, v77
	v_exp_f32_e32 v78, v78
	v_exp_f32_e32 v79, v79
	s_waitcnt lgkmcnt(0)
; #define ALAS __attribute__((address_space(3)))
; __device__ __forceinline__ s16x4 vtr(const ALAS unsigned char* p) { return __builtin_bit_cast(s16x4, __builtin_amdgcn_ds_read_tr16_b64_v4i16((ALAS s16x4*)p)); }
; #define AMFMA(a, b, c) __builtin_amdgcn_mfma_f32_32x32x16_bf16((a), (b), (c), 0, 0, 0)
; template <bool SUB> __device__ __forceinline__ void attn_unit_r2b(const AU& u, ALAS unsigned char* lds, float mb2) {
;     ...
;             R2B_SOFT(Sa0, Sa1, paa, la);
;             __builtin_amdgcn_sched_barrier(0);
;             R2B_SOFT(Sb0, Sb1, pab, lb);
;     ...
; #pragma unroll
;             for (int ks = 0; ks < 4; ++ks) {
;                 const s16x4 lo0 = vtr(vb + ks * 16 * VP), hi0 = vtr(vb + (ks * 16 + 8) * VP), lo1 = vtr(vb + ks * 16 * VP + 64), hi1 = vtr(vb + (ks * 16 + 8) * VP + 64);
;                 const bf16x8 vf0 = __builtin_shufflevector(lo0, hi0, 0, 1, 2, 3, 4, 5, 6, 7), vf1 = __builtin_shufflevector(lo1, hi1, 0, 1, 2, 3, 4, 5, 6, 7);
;                 oa0 = AMFMA(paa[ks], vf0, oa0); oa1 = AMFMA(paa[ks], vf1, oa1); ob0 = AMFMA(pab[ks], vf0, ob0); ob1 = AMFMA(pab[ks], vf1, ob1);
;             }
;         }
;         if (t + 1 < NT) { *(ALAS u32x4*)(lds + (cur ^ 1) * KBUF + kl0) = rk0; if (k2) *(ALAS u32x4*)(lds + (cur ^ 1) * KBUF + kl1) = rk1; *(ALAS u32x4*)(lds + (cur ^ 1) * VBUF + vl) = rv; }
	v_mfma_f32_32x32x16_bf16 v[80:95], v[218:221], v[176:179], 0
	ds_read_b128 v[176:179], v193 offset:50176
	v_cvt_pk_bf16_f32 v218, v96, v97
	v_cvt_pk_bf16_f32 v219, v98, v99
	v_cvt_pk_bf16_f32 v220, v100, v101
	v_cvt_pk_bf16_f32 v221, v102, v103
	v_mfma_f32_32x32x16_bf16 v[80:95], v[222:225], v[180:183], v[80:95]
	v_cvt_pk_bf16_f32 v222, v64, v65
	v_cvt_pk_bf16_f32 v223, v66, v67
	v_cvt_pk_bf16_f32 v224, v68, v69
	v_cvt_pk_bf16_f32 v225, v70, v71
	v_exp_f32_e32 v112, v112
	v_exp_f32_e32 v113, v113
	v_mfma_f32_32x32x16_bf16 v[80:95], v[226:229], v[184:187], v[80:95]
	v_cvt_pk_bf16_f32 v226, v104, v105
	v_cvt_pk_bf16_f32 v227, v106, v107
	v_cvt_pk_bf16_f32 v228, v108, v109
	v_cvt_pk_bf16_f32 v229, v110, v111
	v_exp_f32_e32 v114, v114
	v_exp_f32_e32 v115, v115
	ds_read_b64_tr_b16 v[184:185], v197 offset:26624
	ds_read_b64_tr_b16 v[186:187], v197 offset:27776
	v_mfma_f32_32x32x16_bf16 v[80:95], v[230:233], v[248:251], v[80:95]
	v_cvt_pk_bf16_f32 v230, v72, v73
	v_cvt_pk_bf16_f32 v231, v74, v75
	v_cvt_pk_bf16_f32 v232, v76, v77
	v_cvt_pk_bf16_f32 v233, v78, v79
	v_exp_f32_e32 v116, v116
	v_exp_f32_e32 v117, v117
	ds_read_b64_tr_b16 v[248:249], v197 offset:26688
	ds_read_b64_tr_b16 v[250:251], v197 offset:27840
	v_mfma_f32_32x32x16_bf16 v[80:95], v[234:237], v[244:247], v[80:95]
	v_exp_f32_e32 v118, v118
	v_exp_f32_e32 v119, v119
	v_exp_f32_e32 v120, v120
	v_exp_f32_e32 v121, v121
	ds_read_b64_tr_b16 v[244:245], v197 offset:28928
	ds_read_b64_tr_b16 v[246:247], v197 offset:30080
	s_waitcnt lgkmcnt(6)
	v_mfma_f32_32x32x16_bf16 v[80:95], v[238:241], v[176:179], v[80:95]
	v_exp_f32_e32 v122, v122
	v_exp_f32_e32 v123, v123
	v_exp_f32_e32 v124, v124
	v_exp_f32_e32 v125, v125
	s_waitcnt lgkmcnt(2)
	v_mfma_f32_32x32x16_bf16 v[32:47], v[218:221], v[184:187], v[32:47]
	v_exp_f32_e32 v126, v126
	v_exp_f32_e32 v127, v127
	v_cvt_pk_bf16_f32 v234, v112, v113
	v_cvt_pk_bf16_f32 v235, v114, v115
	v_cvt_pk_bf16_f32 v236, v116, v117
	v_cvt_pk_bf16_f32 v237, v118, v119
	v_mfma_f32_32x32x16_bf16 v[48:63], v[218:221], v[248:251], v[48:63]
	v_exp_f32_e32 v80, v80
	v_exp_f32_e32 v81, v81
	v_exp_f32_e32 v82, v82
	v_exp_f32_e32 v83, v83
	v_mfma_f32_32x32x16_bf16 v[0:15], v[222:225], v[184:187], v[0:15]
	ds_read_b64_tr_b16 v[184:185], v197 offset:28992
	ds_read_b64_tr_b16 v[186:187], v197 offset:30144
	v_exp_f32_e32 v84, v84
	v_exp_f32_e32 v85, v85
	v_exp_f32_e32 v86, v86
	v_exp_f32_e32 v87, v87
	v_mfma_f32_32x32x16_bf16 v[16:31], v[222:225], v[248:251], v[16:31]
	ds_read_b64_tr_b16 v[248:249], v197 offset:31232
	ds_read_b64_tr_b16 v[250:251], v197 offset:32384
	v_exp_f32_e32 v88, v88
	v_exp_f32_e32 v89, v89
	v_exp_f32_e32 v90, v90
	v_exp_f32_e32 v91, v91
	s_waitcnt lgkmcnt(2)
	v_mfma_f32_32x32x16_bf16 v[32:47], v[226:229], v[244:247], v[32:47]
	v_exp_f32_e32 v92, v92
	v_exp_f32_e32 v93, v93
	v_exp_f32_e32 v94, v94
	v_exp_f32_e32 v95, v95
	v_mfma_f32_32x32x16_bf16 v[48:63], v[226:229], v[184:187], v[48:63]
	v_cvt_pk_bf16_f32 v176, v120, v121
	v_cvt_pk_bf16_f32 v177, v122, v123
	v_cvt_pk_bf16_f32 v178, v124, v125
	v_cvt_pk_bf16_f32 v179, v126, v127
	v_cvt_pk_bf16_f32 v238, v80, v81
	v_cvt_pk_bf16_f32 v239, v82, v83
	v_cvt_pk_bf16_f32 v240, v84, v85
	v_cvt_pk_bf16_f32 v241, v86, v87
	v_mfma_f32_32x32x16_bf16 v[0:15], v[230:233], v[244:247], v[0:15]
	ds_read_b64_tr_b16 v[244:245], v197 offset:31296
	ds_read_b64_tr_b16 v[246:247], v197 offset:32448
	v_cvt_pk_bf16_f32 v180, v88, v89
	v_cvt_pk_bf16_f32 v181, v90, v91
	v_cvt_pk_bf16_f32 v182, v92, v93
	v_cvt_pk_bf16_f32 v183, v94, v95
	v_add_f32_e32 v164, v96, v164
	v_add_f32_e32 v165, v64, v165
	v_add_f32_e32 v164, v97, v164
	v_mfma_f32_32x32x16_bf16 v[16:31], v[230:233], v[184:187], v[16:31]
	ds_read_b64_tr_b16 v[184:185], v197 offset:33536
	ds_read_b64_tr_b16 v[186:187], v197 offset:34688
	v_add_f32_e32 v165, v65, v165
	v_add_f32_e32 v164, v98, v164
	v_add_f32_e32 v165, v66, v165
	v_add_f32_e32 v164, v99, v164
	v_add_f32_e32 v165, v67, v165
	s_waitcnt lgkmcnt(2)
	v_mfma_f32_32x32x16_bf16 v[32:47], v[234:237], v[248:251], v[32:47]
	v_add_f32_e32 v164, v100, v164
	v_add_f32_e32 v165, v68, v165
	v_add_f32_e32 v164, v101, v164
	v_add_f32_e32 v165, v69, v165
	v_add_f32_e32 v164, v102, v164
	v_add_f32_e32 v165, v70, v165
	v_mfma_f32_32x32x16_bf16 v[48:63], v[234:237], v[244:247], v[48:63]
	v_add_f32_e32 v164, v103, v164
	v_add_f32_e32 v165, v71, v165
	v_add_f32_e32 v164, v104, v164
	v_add_f32_e32 v165, v72, v165
	v_add_f32_e32 v164, v105, v164
	v_add_f32_e32 v165, v73, v165
	v_mfma_f32_32x32x16_bf16 v[0:15], v[238:241], v[248:251], v[0:15]
	ds_read_b64_tr_b16 v[248:249], v197 offset:33600
	ds_read_b64_tr_b16 v[250:251], v197 offset:34752
	v_add_f32_e32 v164, v106, v164
	v_add_f32_e32 v165, v74, v165
	v_add_f32_e32 v164, v107, v164
	v_add_f32_e32 v165, v75, v165
	v_add_f32_e32 v164, v108, v164
	v_mfma_f32_32x32x16_bf16 v[16:31], v[238:241], v[244:247], v[16:31]
	v_add_f32_e32 v165, v76, v165
	v_add_f32_e32 v164, v109, v164
	v_add_f32_e32 v165, v77, v165
	v_add_f32_e32 v164, v110, v164
	v_add_f32_e32 v165, v78, v165
	v_add_f32_e32 v164, v111, v164
	s_waitcnt lgkmcnt(0)
	v_mfma_f32_32x32x16_bf16 v[32:47], v[176:179], v[184:187], v[32:47]
	v_add_f32_e32 v165, v79, v165
	v_mfma_f32_32x32x16_bf16 v[48:63], v[176:179], v[248:251], v[48:63]
	s_waitcnt vmcnt(0)
	ds_write_b128 v194, v[152:155] offset:13312
	s_and_saveexec_b64 s[58:59], s[40:41]
	s_cbranch_execz .Lr2b_nok2wA
	ds_write_b128 v195, v[156:159] offset:13312

; #define ALAS __attribute__((address_space(3)))
; #define AMFMA(a, b, c) __builtin_amdgcn_mfma_f32_32x32x16_bf16((a), (b), (c), 0, 0, 0)
; template <bool SUB> __device__ __forceinline__ void attn_unit_r2b(const AU& u, ALAS unsigned char* lds, float mb2) {
;     ...
;         if (t + 1 < NT) { const size_t ro = (size_t)(t + 1) * 64; rk0 = *(const u32x4*)(kg0 + ro * u.krs); if (k2) rk1 = *(const u32x4*)(kg1 + ro * u.krs); rv = *(const u32x4*)(vg + ro * u.vrs); }
;         {
;             const ALAS unsigned char* kb = lds + cur * KBUF + r * KP + h * 16;
;             const ALAS unsigned char* vb = lds + V_OFF + cur * VBUF + (4 * h + ((lane & 15) >> 2)) * VP + ((lane >> 4) & 1) * 32 + (lane & 3) * 8;
;             bf16x8 paa[4], pab[4];
;             f32x16 Sa0, Sa1, Sb0, Sb1;
; #pragma unroll
;             for (int i = 0; i < 16; ++i) { Sa0[i] = 0.f; Sa1[i] = 0.f; Sb0[i] = 0.f; Sb1[i] = 0.f; }
; #pragma unroll
;             for (int d0 = 0; d0 < 6; ++d0) {
;                 const bf16x8 k0 = *(const ALAS bf16x8*)(kb + d0 * 32), k1 = *(const ALAS bf16x8*)(kb + 32 * KP + d0 * 32); const bf16x8 qbv = *(const ALAS bf16x8*)(qbl + d0 * 1024);
;                 Sa0 = AMFMA(k0, qa[d0], Sa0); Sa1 = AMFMA(k1, qa[d0], Sa1); Sb0 = AMFMA(k0, qbv, Sb0); Sb1 = AMFMA(k1, qbv, Sb1);
;                 if (d0 & 1) __builtin_amdgcn_sched_barrier(0);
;             }
.Lr2b_noloadB:
	ds_read_b128 v[218:221], v168 offset:13312
	ds_read_b128 v[222:225], v168 offset:13344
	ds_read_b128 v[226:229], v168 offset:13376
	ds_read_b128 v[230:233], v168 offset:13408
	ds_read_b128 v[234:237], v168 offset:13440
	ds_read_b128 v[238:241], v168 offset:13472
	ds_read_b128 v[176:179], v193 offset:45056
	ds_read_b128 v[180:183], v193 offset:46080
	ds_read_b128 v[184:187], v193 offset:47104
	ds_read_b128 v[248:251], v193 offset:48128
	ds_read_b128 v[244:247], v193 offset:49152
	v_add_f32_e32 v242, v112, v242
	v_add_f32_e32 v243, v80, v243
	v_add_f32_e32 v242, v113, v242
	v_add_f32_e32 v243, v81, v243
	v_add_f32_e32 v242, v114, v242
	v_add_f32_e32 v243, v82, v243
	v_add_f32_e32 v242, v115, v242
	v_add_f32_e32 v243, v83, v243
	v_add_f32_e32 v242, v116, v242
	v_add_f32_e32 v243, v84, v243
	v_add_f32_e32 v242, v117, v242
	v_add_f32_e32 v243, v85, v243
	v_add_f32_e32 v242, v118, v242
	v_add_f32_e32 v243, v86, v243
	v_add_f32_e32 v242, v119, v242
	v_add_f32_e32 v243, v87, v243
	v_add_f32_e32 v242, v120, v242
	v_add_f32_e32 v243, v88, v243
	v_add_f32_e32 v242, v121, v242
	v_add_f32_e32 v243, v89, v243
	s_waitcnt lgkmcnt(5)
	v_mfma_f32_32x32x16_bf16 v[96:111], v[218:221], v[128:131], 0
	v_lshl_add_u64 v[166:167], v[166:167], 0, s[8:9]
	v_mfma_f32_32x32x16_bf16 v[96:111], v[222:225], v[132:135], v[96:111]
	v_lshl_add_u64 v[172:173], v[172:173], 0, s[12:13]
	v_mfma_f32_32x32x16_bf16 v[96:111], v[226:229], v[136:139], v[96:111]
	v_lshl_add_u64 v[174:175], v[174:175], 0, s[12:13]
	v_mfma_f32_32x32x16_bf16 v[96:111], v[230:233], v[140:143], v[96:111]
	v_mfma_f32_32x32x16_bf16 v[96:111], v[234:237], v[144:147], v[96:111]
	v_add_f32_e32 v242, v122, v242
	v_add_f32_e32 v243, v90, v243
	v_add_f32_e32 v242, v123, v242
	v_add_f32_e32 v243, v91, v243
	v_mfma_f32_32x32x16_bf16 v[96:111], v[238:241], v[148:151], v[96:111]
	v_add_f32_e32 v242, v124, v242
	v_add_f32_e32 v243, v92, v243
	v_add_f32_e32 v242, v125, v242
	v_add_f32_e32 v243, v93, v243
	s_waitcnt lgkmcnt(0)
	v_mfma_f32_32x32x16_bf16 v[64:79], v[218:221], v[176:179], 0
	ds_read_b128 v[176:179], v193 offset:50176
	ds_read_b128 v[218:221], v168 offset:19968
	v_add_f32_e32 v242, v126, v242
	v_add_f32_e32 v243, v94, v243
	v_add_f32_e32 v242, v127, v242
	v_add_f32_e32 v243, v95, v243
	v_mfma_f32_32x32x16_bf16 v[64:79], v[222:225], v[180:183], v[64:79]
	ds_read_b128 v[222:225], v168 offset:20000
	v_exp_f32_e32 v96, v96
	v_exp_f32_e32 v97, v97
	v_mfma_f32_32x32x16_bf16 v[64:79], v[226:229], v[184:187], v[64:79]
	ds_read_b128 v[226:229], v168 offset:20032
	v_exp_f32_e32 v98, v98
	v_exp_f32_e32 v99, v99
	v_mfma_f32_32x32x16_bf16 v[64:79], v[230:233], v[248:251], v[64:79]
	ds_read_b128 v[230:233], v168 offset:20064
	v_exp_f32_e32 v100, v100
	v_exp_f32_e32 v101, v101
	v_mfma_f32_32x32x16_bf16 v[64:79], v[234:237], v[244:247], v[64:79]
	ds_read_b128 v[234:237], v168 offset:20096
	v_exp_f32_e32 v102, v102
	v_exp_f32_e32 v103, v103
	s_waitcnt lgkmcnt(5)
	v_mfma_f32_32x32x16_bf16 v[64:79], v[238:241], v[176:179], v[64:79]
	ds_read_b128 v[238:241], v168 offset:20128
	ds_read_b128 v[176:179], v193 offset:45056
	v_exp_f32_e32 v104, v104
	v_exp_f32_e32 v105, v105
	v_exp_f32_e32 v106, v106
	v_exp_f32_e32 v107, v107
	s_waitcnt lgkmcnt(1)
	v_mfma_f32_32x32x16_bf16 v[112:127], v[218:221], v[128:131], 0
	v_exp_f32_e32 v108, v108
	v_exp_f32_e32 v109, v109
	v_exp_f32_e32 v110, v110
	v_exp_f32_e32 v111, v111
	v_mfma_f32_32x32x16_bf16 v[112:127], v[222:225], v[132:135], v[112:127]
	v_exp_f32_e32 v64, v64
	v_exp_f32_e32 v65, v65
	v_exp_f32_e32 v66, v66
	v_mfma_f32_32x32x16_bf16 v[112:127], v[226:229], v[136:139], v[112:127]
	v_exp_f32_e32 v67, v67
	v_exp_f32_e32 v68, v68
	v_exp_f32_e32 v69, v69
	v_mfma_f32_32x32x16_bf16 v[112:127], v[230:233], v[140:143], v[112:127]
	v_exp_f32_e32 v70, v70
	v_exp_f32_e32 v71, v71
	v_exp_f32_e32 v72, v72
	v_mfma_f32_32x32x16_bf16 v[112:127], v[234:237], v[144:147], v[112:127]
	v_exp_f32_e32 v73, v73
	v_exp_f32_e32 v74, v74
	v_exp_f32_e32 v75, v75
	v_mfma_f32_32x32x16_bf16 v[112:127], v[238:241], v[148:151], v[112:127]
	v_exp_f32_e32 v76, v76
	v_exp_f32_e32 v77, v77
	v_exp_f32_e32 v78, v78
	v_exp_f32_e32 v79, v79
	s_waitcnt lgkmcnt(0)
; #define ALAS __attribute__((address_space(3)))
; __device__ __forceinline__ s16x4 vtr(const ALAS unsigned char* p) { return __builtin_bit_cast(s16x4, __builtin_amdgcn_ds_read_tr16_b64_v4i16((ALAS s16x4*)p)); }
; #define AMFMA(a, b, c) __builtin_amdgcn_mfma_f32_32x32x16_bf16((a), (b), (c), 0, 0, 0)
; template <bool SUB> __device__ __forceinline__ void attn_unit_r2b(const AU& u, ALAS unsigned char* lds, float mb2) {
;     ...
;             R2B_SOFT(Sa0, Sa1, paa, la);
;             __builtin_amdgcn_sched_barrier(0);
;             R2B_SOFT(Sb0, Sb1, pab, lb);
;     ...
; #pragma unroll
;             for (int ks = 0; ks < 4; ++ks) {
;                 const s16x4 lo0 = vtr(vb + ks * 16 * VP), hi0 = vtr(vb + (ks * 16 + 8) * VP), lo1 = vtr(vb + ks * 16 * VP + 64), hi1 = vtr(vb + (ks * 16 + 8) * VP + 64);
;                 const bf16x8 vf0 = __builtin_shufflevector(lo0, hi0, 0, 1, 2, 3, 4, 5, 6, 7), vf1 = __builtin_shufflevector(lo1, hi1, 0, 1, 2, 3, 4, 5, 6, 7);
;                 oa0 = AMFMA(paa[ks], vf0, oa0); oa1 = AMFMA(paa[ks], vf1, oa1); ob0 = AMFMA(pab[ks], vf0, ob0); ob1 = AMFMA(pab[ks], vf1, ob1);
;             }
;         }
;         if (t + 1 < NT) { *(ALAS u32x4*)(lds + (cur ^ 1) * KBUF + kl0) = rk0; if (k2) *(ALAS u32x4*)(lds + (cur ^ 1) * KBUF + kl1) = rk1; *(ALAS u32x4*)(lds + (cur ^ 1) * VBUF + vl) = rv; }
	v_mfma_f32_32x32x16_bf16 v[80:95], v[218:221], v[176:179], 0
	ds_read_b128 v[176:179], v193 offset:50176
	v_cvt_pk_bf16_f32 v218, v96, v97
	v_cvt_pk_bf16_f32 v219, v98, v99
	v_cvt_pk_bf16_f32 v220, v100, v101
	v_cvt_pk_bf16_f32 v221, v102, v103
	v_mfma_f32_32x32x16_bf16 v[80:95], v[222:225], v[180:183], v[80:95]
	v_cvt_pk_bf16_f32 v222, v64, v65
	v_cvt_pk_bf16_f32 v223, v66, v67
	v_cvt_pk_bf16_f32 v224, v68, v69
	v_cvt_pk_bf16_f32 v225, v70, v71
	v_exp_f32_e32 v112, v112
	v_exp_f32_e32 v113, v113
	v_mfma_f32_32x32x16_bf16 v[80:95], v[226:229], v[184:187], v[80:95]
	v_cvt_pk_bf16_f32 v226, v104, v105
	v_cvt_pk_bf16_f32 v227, v106, v107
	v_cvt_pk_bf16_f32 v228, v108, v109
	v_cvt_pk_bf16_f32 v229, v110, v111
	v_exp_f32_e32 v114, v114
	v_exp_f32_e32 v115, v115
	ds_read_b64_tr_b16 v[184:185], v197 offset:35840
	ds_read_b64_tr_b16 v[186:187], v197 offset:36992
	v_mfma_f32_32x32x16_bf16 v[80:95], v[230:233], v[248:251], v[80:95]
	v_cvt_pk_bf16_f32 v230, v72, v73
	v_cvt_pk_bf16_f32 v231, v74, v75
	v_cvt_pk_bf16_f32 v232, v76, v77
	v_cvt_pk_bf16_f32 v233, v78, v79
	v_exp_f32_e32 v116, v116
	v_exp_f32_e32 v117, v117
	ds_read_b64_tr_b16 v[248:249], v197 offset:35904
	ds_read_b64_tr_b16 v[250:251], v197 offset:37056
	v_mfma_f32_32x32x16_bf16 v[80:95], v[234:237], v[244:247], v[80:95]
	v_exp_f32_e32 v118, v118
	v_exp_f32_e32 v119, v119
	v_exp_f32_e32 v120, v120
	v_exp_f32_e32 v121, v121
	ds_read_b64_tr_b16 v[244:245], v197 offset:38144
	ds_read_b64_tr_b16 v[246:247], v197 offset:39296
	s_waitcnt lgkmcnt(6)
	v_mfma_f32_32x32x16_bf16 v[80:95], v[238:241], v[176:179], v[80:95]
	v_exp_f32_e32 v122, v122
	v_exp_f32_e32 v123, v123
	v_exp_f32_e32 v124, v124
	v_exp_f32_e32 v125, v125
	s_waitcnt lgkmcnt(2)
	v_mfma_f32_32x32x16_bf16 v[32:47], v[218:221], v[184:187], v[32:47]
	v_exp_f32_e32 v126, v126
	v_exp_f32_e32 v127, v127
	v_cvt_pk_bf16_f32 v234, v112, v113
	v_cvt_pk_bf16_f32 v235, v114, v115
	v_cvt_pk_bf16_f32 v236, v116, v117
	v_cvt_pk_bf16_f32 v237, v118, v119
	v_mfma_f32_32x32x16_bf16 v[48:63], v[218:221], v[248:251], v[48:63]
	v_exp_f32_e32 v80, v80
	v_exp_f32_e32 v81, v81
	v_exp_f32_e32 v82, v82
	v_exp_f32_e32 v83, v83
	v_mfma_f32_32x32x16_bf16 v[0:15], v[222:225], v[184:187], v[0:15]
	ds_read_b64_tr_b16 v[184:185], v197 offset:38208
	ds_read_b64_tr_b16 v[186:187], v197 offset:39360
	v_exp_f32_e32 v84, v84
	v_exp_f32_e32 v85, v85
	v_exp_f32_e32 v86, v86
	v_exp_f32_e32 v87, v87
	v_mfma_f32_32x32x16_bf16 v[16:31], v[222:225], v[248:251], v[16:31]
	ds_read_b64_tr_b16 v[248:249], v197 offset:40448
	ds_read_b64_tr_b16 v[250:251], v197 offset:41600
	v_exp_f32_e32 v88, v88
	v_exp_f32_e32 v89, v89
	v_exp_f32_e32 v90, v90
	v_exp_f32_e32 v91, v91
	s_waitcnt lgkmcnt(2)
	v_mfma_f32_32x32x16_bf16 v[32:47], v[226:229], v[244:247], v[32:47]
	v_exp_f32_e32 v92, v92
	v_exp_f32_e32 v93, v93
	v_exp_f32_e32 v94, v94
	v_exp_f32_e32 v95, v95
	v_mfma_f32_32x32x16_bf16 v[48:63], v[226:229], v[184:187], v[48:63]
	v_cvt_pk_bf16_f32 v176, v120, v121
	v_cvt_pk_bf16_f32 v177, v122, v123
	v_cvt_pk_bf16_f32 v178, v124, v125
	v_cvt_pk_bf16_f32 v179, v126, v127
	v_cvt_pk_bf16_f32 v238, v80, v81
	v_cvt_pk_bf16_f32 v239, v82, v83
	v_cvt_pk_bf16_f32 v240, v84, v85
	v_cvt_pk_bf16_f32 v241, v86, v87
	v_mfma_f32_32x32x16_bf16 v[0:15], v[230:233], v[244:247], v[0:15]
	ds_read_b64_tr_b16 v[244:245], v197 offset:40512
	ds_read_b64_tr_b16 v[246:247], v197 offset:41664
	v_cvt_pk_bf16_f32 v180, v88, v89
	v_cvt_pk_bf16_f32 v181, v90, v91
	v_cvt_pk_bf16_f32 v182, v92, v93
	v_cvt_pk_bf16_f32 v183, v94, v95
	v_add_f32_e32 v164, v96, v164
	v_add_f32_e32 v165, v64, v165
	v_add_f32_e32 v164, v97, v164
	v_mfma_f32_32x32x16_bf16 v[16:31], v[230:233], v[184:187], v[16:31]
	ds_read_b64_tr_b16 v[184:185], v197 offset:42752
	ds_read_b64_tr_b16 v[186:187], v197 offset:43904
	v_add_f32_e32 v165, v65, v165
	v_add_f32_e32 v164, v98, v164
	v_add_f32_e32 v165, v66, v165
	v_add_f32_e32 v164, v99, v164
	v_add_f32_e32 v165, v67, v165
	s_waitcnt lgkmcnt(2)
	v_mfma_f32_32x32x16_bf16 v[32:47], v[234:237], v[248:251], v[32:47]
	v_add_f32_e32 v164, v100, v164
	v_add_f32_e32 v165, v68, v165
	v_add_f32_e32 v164, v101, v164
	v_add_f32_e32 v165, v69, v165
	v_add_f32_e32 v164, v102, v164
	v_add_f32_e32 v165, v70, v165
	v_mfma_f32_32x32x16_bf16 v[48:63], v[234:237], v[244:247], v[48:63]
	v_add_f32_e32 v164, v103, v164
	v_add_f32_e32 v165, v71, v165
	v_add_f32_e32 v164, v104, v164
	v_add_f32_e32 v165, v72, v165
	v_add_f32_e32 v164, v105, v164
	v_add_f32_e32 v165, v73, v165
	v_mfma_f32_32x32x16_bf16 v[0:15], v[238:241], v[248:251], v[0:15]
	ds_read_b64_tr_b16 v[248:249], v197 offset:42816
	ds_read_b64_tr_b16 v[250:251], v197 offset:43968
	v_add_f32_e32 v164, v106, v164
	v_add_f32_e32 v165, v74, v165
	v_add_f32_e32 v164, v107, v164
	v_add_f32_e32 v165, v75, v165
	v_add_f32_e32 v164, v108, v164
	v_mfma_f32_32x32x16_bf16 v[16:31], v[238:241], v[244:247], v[16:31]
	v_add_f32_e32 v165, v76, v165
	v_add_f32_e32 v164, v109, v164
	v_add_f32_e32 v165, v77, v165
	v_add_f32_e32 v164, v110, v164
	v_add_f32_e32 v165, v78, v165
	v_add_f32_e32 v164, v111, v164
	s_waitcnt lgkmcnt(0)
	v_mfma_f32_32x32x16_bf16 v[32:47], v[176:179], v[184:187], v[32:47]
	v_add_f32_e32 v165, v79, v165
	s_andn2_b64 vcc, exec, s[56:57]
	v_mfma_f32_32x32x16_bf16 v[48:63], v[176:179], v[248:251], v[48:63]
	s_cbranch_vccnz .Lr2b_nowriteB
	s_waitcnt vmcnt(0)
	ds_write_b128 v194, v[152:155] offset:0
	s_and_saveexec_b64 s[58:59], s[40:41]
	s_cbranch_execz .Lr2b_nok2wB
	ds_write_b128 v195, v[156:159] offset:0
